# mLSTM: per-chunk q/k row prefetch (22 loads) de-serialised: one address + pointer walking by the row pitch instead of 11 exec-masked blocks each rebuilding a 64-bit address (126 -> 37 instructions)
# speedup vs baseline: 1.0055x; 1.0055x over previous
; #define LAS __attribute__((address_space(3)))
; __device__ __forceinline__ unsigned pk2(float lo, float hi) { const f32x2 v = {lo, hi}; const bf16x2n b = __builtin_convertvector(v, bf16x2n); return __builtin_bit_cast(unsigned, b); }
; __device__ __forceinline__ float siluf_(float x) { return x * rcp_(1.0f + __expf(-x)); }
; __device__ __forceinline__ void ml_block(KP p, int e, int b, int hd, int half, LAS unsigned char* lds, const bf16_t* P, bf16_t* YB) {
;     ...
;         {
;             const float blast = Bc[63];
;             unsigned vr[8];
; #pragma unroll
;             for (int i = 0; i < 8; ++i) vr[i] = *(const unsigned*)(P + (rbase + tb + tg * 8 + i) * NPROJ + 2048 + hd * 128 + 2 * d2);
;             f32x2 wq[4], wk[4];
; #pragma unroll
;             for (int tp = 0; tp < 4; ++tp) { wq[tp] = *(const LAS f32x2*)(CW + tp * 256 + 2 * d2); wk[tp] = *(const LAS f32x2*)(CW + tp * 256 + 128 + 2 * d2); }
;             const f32x2 bq = *(const LAS f32x2*)(CW + 1024 + 2 * d2), bk = *(const LAS f32x2*)(CW + 1024 + 128 + 2 * d2);
;             float kw0[8], kw1[8];
; #pragma unroll
;             for (int i = 0; i < 8; ++i) {
;                 const int j = tg * 8 + i;
;                 f32x2 aq = bq, ak = bk;
; #pragma unroll
;                 for (int tp = 0; tp < 4; ++tp) {
;                     const f32x2 xq = {__uint_as_float(qr[i + tp] << 16), __uint_as_float(qr[i + tp] & 0xFFFF0000u)}, xk = {__uint_as_float(kr[i + tp] << 16), __uint_as_float(kr[i + tp] & 0xFFFF0000u)};
;                     aq = wq[tp] * xq + aq; ak = wk[tp] * xk + ak;
;                 }
;                 const float q0 = siluf_(aq.x) * qscale, q1 = siluf_(aq.y) * qscale, k0 = siluf_(ak.x), k1 = siluf_(ak.y);
;                 *(LAS unsigned*)(Qs + j * 136 + 2 * d2) = pk2(q0, q1);
;                 *(LAS unsigned*)(Ks + j * 136 + 2 * d2) = pk2(k0, k1);
;                 const float wkj = __expf(blast - Bc[j] + Ip[j]);
;                 kw0[i] = wkj * k0; kw1[i] = wkj * k1;
;             }
.LBB0_327:
	s_and_b32 s7, s53, 1
	s_add_i32 s33, 0, 0x1de00
	s_cmpk_lg_i32 s52, 0xfc0
	s_cselect_b64 s[42:43], -1, 0
	s_cmp_eq_u32 s7, 0
	s_cselect_b64 s[44:45], -1, 0
	s_and_b64 s[46:47], s[44:45], exec
	s_cselect_b32 s7, s60, s61
	v_mov_b32_e32 v42, s7
	ds_read_b32 v184, v42
	v_lshl_add_u64 v[42:43], s[50:51], 0, v[102:103]
	v_add_co_u32_e32 v44, vcc, s64, v42
	s_cselect_b32 s56, s33, s4
	s_nop 0
	v_addc_co_u32_e32 v45, vcc, 0, v43, vcc
	s_mov_b32 s33, 0x12602000
	global_load_dword v178, v[44:45], off
	v_add_co_u32_e32 v44, vcc, s33, v42
	s_mov_b32 s33, 0x12605000
	s_nop 0
	v_addc_co_u32_e32 v45, vcc, 0, v43, vcc
	global_load_dword v179, v[44:45], off offset:2560
	v_add_co_u32_e32 v44, vcc, s65, v42
	s_waitcnt vmcnt(4)
	v_lshlrev_b32_e32 v104, 16, v116
	v_addc_co_u32_e32 v45, vcc, 0, v43, vcc
	global_load_dword v180, v[44:45], off offset:1024
	v_add_co_u32_e32 v44, vcc, s33, v42
	s_mov_b32 s33, 0x12607000
	s_nop 0
	v_addc_co_u32_e32 v45, vcc, 0, v43, vcc
	global_load_dword v181, v[44:45], off offset:3584
	v_add_co_u32_e32 v44, vcc, s33, v42
	s_mov_b32 s33, 0x1260a000
	s_nop 0
	v_addc_co_u32_e32 v45, vcc, 0, v43, vcc
	global_load_dword v182, v[44:45], off offset:2048
	v_add_co_u32_e32 v44, vcc, s66, v42
	v_and_b32_e32 v105, 0xffff0000, v116
	s_nop 0
	v_addc_co_u32_e32 v45, vcc, 0, v43, vcc
	global_load_dword v183, v[44:45], off offset:512
	v_add_co_u32_e32 v44, vcc, s33, v42
	s_mov_b32 s33, 0x1260c000
	s_nop 0
	v_addc_co_u32_e32 v45, vcc, 0, v43, vcc
	v_add_co_u32_e32 v42, vcc, s33, v42
	global_load_dword v185, v[44:45], off offset:3072
	s_nop 0
	v_addc_co_u32_e32 v43, vcc, 0, v43, vcc
	global_load_dword v186, v[42:43], off offset:1536
	ds_read_b64 v[58:59], v151
	ds_read_b64 v[60:61], v152
	ds_read_b64 v[66:67], v153
	ds_read_b64 v[68:69], v154
	ds_read_b64 v[70:71], v155
	ds_read_b64 v[72:73], v156
	ds_read_b64 v[62:63], v157
	ds_read_b64 v[64:65], v158
	ds_read_b64 v[74:75], v138
	ds_read_b64 v[76:77], v139
	v_lshlrev_b32_e32 v42, 16, v113
	v_and_b32_e32 v43, 0xffff0000, v113
	v_lshlrev_b32_e32 v108, 16, v118
	s_waitcnt lgkmcnt(1)
	v_pk_fma_f32 v[42:43], v[58:59], v[42:43], v[74:75]
	v_and_b32_e32 v109, 0xffff0000, v118
	v_pk_fma_f32 v[42:43], v[66:67], v[104:105], v[42:43]
	v_lshlrev_b32_e32 v78, 16, v120
	v_pk_fma_f32 v[42:43], v[70:71], v[108:109], v[42:43]
	v_and_b32_e32 v79, 0xffff0000, v120
	v_pk_fma_f32 v[42:43], v[62:63], v[78:79], v[42:43]
	s_waitcnt vmcnt(9)
	v_lshlrev_b32_e32 v44, 16, v115
	v_mul_f32_e32 v46, 0xbfb8aa3b, v42
	v_mul_f32_e32 v47, 0xbfb8aa3b, v43
	v_exp_f32_e32 v46, v46
	v_exp_f32_e32 v47, v47
	v_and_b32_e32 v45, 0xffff0000, v115
	s_waitcnt lgkmcnt(0)
	v_pk_fma_f32 v[44:45], v[60:61], v[44:45], v[76:77]
	v_add_f32_e32 v46, 1.0, v46
	v_add_f32_e32 v47, 1.0, v47
	v_lshlrev_b32_e32 v106, 16, v117
	v_and_b32_e32 v107, 0xffff0000, v117
	v_rcp_f32_e32 v46, v46
	v_rcp_f32_e32 v47, v47
	v_pk_fma_f32 v[44:45], v[68:69], v[106:107], v[44:45]
	v_lshlrev_b32_e32 v110, 16, v119
	v_and_b32_e32 v111, 0xffff0000, v119
	v_pk_fma_f32 v[44:45], v[72:73], v[110:111], v[44:45]
	v_lshlrev_b32_e32 v80, 16, v121
	v_and_b32_e32 v81, 0xffff0000, v121
	v_pk_fma_f32 v[44:45], v[64:65], v[80:81], v[44:45]
	v_pk_mul_f32 v[42:43], v[42:43], v[46:47]
	v_mul_f32_e32 v46, 0xbfb8aa3b, v44
	v_mul_f32_e32 v47, 0xbfb8aa3b, v45
	v_exp_f32_e32 v46, v46
	v_exp_f32_e32 v47, v47
	v_pk_mul_f32 v[42:43], v[42:43], s[80:81] op_sel_hi:[1,0]
	s_cselect_b32 s69, s62, s63
	v_add_f32_e32 v46, 1.0, v46
	v_add_f32_e32 v47, 1.0, v47
	v_rcp_f32_e32 v46, v46
	v_rcp_f32_e32 v47, v47
	v_cvt_pk_bf16_f32 v42, v42, v43
	v_pk_fma_f32 v[104:105], v[58:59], v[104:105], v[74:75]
	v_pk_fma_f32 v[106:107], v[60:61], v[106:107], v[76:77]
	v_pk_mul_f32 v[188:189], v[44:45], v[46:47]
	v_lshlrev_b32_e32 v46, 2, v84
	v_cvt_pk_bf16_f32 v43, v188, v189
	ds_write2st64_b32 v92, v42, v43 offset1:68
	v_add_u32_e32 v42, s56, v46
	ds_read_b128 v[50:53], v42
	ds_read_b128 v[42:45], v42 offset:16
	v_add_u32_e32 v46, s69, v46
	ds_read_b128 v[54:57], v46
	ds_read_b128 v[46:49], v46 offset:16
	v_pk_fma_f32 v[104:105], v[66:67], v[108:109], v[104:105]
	s_waitcnt lgkmcnt(3)
	v_sub_f32_e32 v50, v184, v50
	v_pk_fma_f32 v[190:191], v[70:71], v[78:79], v[104:105]
	v_lshlrev_b32_e32 v104, 16, v122
	v_and_b32_e32 v105, 0xffff0000, v122
	v_pk_fma_f32 v[190:191], v[62:63], v[104:105], v[190:191]
	s_waitcnt lgkmcnt(1)
; #define LAS __attribute__((address_space(3)))
; __device__ __forceinline__ unsigned pk2(float lo, float hi) { const f32x2 v = {lo, hi}; const bf16x2n b = __builtin_convertvector(v, bf16x2n); return __builtin_bit_cast(unsigned, b); }
; __device__ __forceinline__ float siluf_(float x) { return x * rcp_(1.0f + __expf(-x)); }
; __device__ __forceinline__ void ml_block(KP p, int e, int b, int hd, int half, LAS unsigned char* lds, const bf16_t* P, bf16_t* YB) {
;     ...
;             for (int i = 0; i < 8; ++i) {
;                 const int j = tg * 8 + i;
;                 f32x2 aq = bq, ak = bk;
; #pragma unroll
;                 for (int tp = 0; tp < 4; ++tp) {
;                     const f32x2 xq = {__uint_as_float(qr[i + tp] << 16), __uint_as_float(qr[i + tp] & 0xFFFF0000u)}, xk = {__uint_as_float(kr[i + tp] << 16), __uint_as_float(kr[i + tp] & 0xFFFF0000u)};
;                     aq = wq[tp] * xq + aq; ak = wk[tp] * xk + ak;
;                 }
;                 const float q0 = siluf_(aq.x) * qscale, q1 = siluf_(aq.y) * qscale, k0 = siluf_(ak.x), k1 = siluf_(ak.y);
;                 *(LAS unsigned*)(Qs + j * 136 + 2 * d2) = pk2(q0, q1);
;                 *(LAS unsigned*)(Ks + j * 136 + 2 * d2) = pk2(k0, k1);
;                 const float wkj = __expf(blast - Bc[j] + Ip[j]);
;                 kw0[i] = wkj * k0; kw1[i] = wkj * k1;
	v_add_f32_e32 v50, v50, v54
	v_mul_f32_e32 v54, 0xbfb8aa3b, v190
	v_exp_f32_e32 v54, v54
	v_pk_fma_f32 v[106:107], v[68:69], v[110:111], v[106:107]
	v_pk_fma_f32 v[108:109], v[58:59], v[108:109], v[74:75]
	v_pk_fma_f32 v[192:193], v[72:73], v[80:81], v[106:107]
	v_add_f32_e32 v54, 1.0, v54
	v_rcp_f32_e32 v210, v54
	v_mul_f32_e32 v54, 0xbfb8aa3b, v191
	v_exp_f32_e32 v54, v54
	v_lshlrev_b32_e32 v106, 16, v123
	v_and_b32_e32 v107, 0xffff0000, v123
	v_pk_fma_f32 v[192:193], v[64:65], v[106:107], v[192:193]
	v_add_f32_e32 v54, 1.0, v54
	v_rcp_f32_e32 v211, v54
	v_mul_f32_e32 v54, 0xbfb8aa3b, v192
	v_exp_f32_e32 v54, v54
	v_sub_f32_e32 v51, v184, v51
	v_pk_mul_f32 v[190:191], v[190:191], v[210:211]
	v_pk_fma_f32 v[108:109], v[66:67], v[78:79], v[108:109]
	v_add_f32_e32 v54, 1.0, v54
	v_rcp_f32_e32 v210, v54
	v_mul_f32_e32 v54, 0xbfb8aa3b, v193
	v_exp_f32_e32 v54, v54
	v_pk_mul_f32 v[190:191], v[190:191], s[80:81] op_sel_hi:[1,0]
	v_add_f32_e32 v51, v51, v55
	v_mul_f32_e32 v50, 0x3fb8aa3b, v50
	v_add_f32_e32 v54, 1.0, v54
	v_rcp_f32_e32 v211, v54
	v_cvt_pk_bf16_f32 v54, v190, v191
	v_mul_f32_e32 v51, 0x3fb8aa3b, v51
	v_exp_f32_e32 v50, v50
	v_pk_mul_f32 v[192:193], v[192:193], v[210:211]
	v_exp_f32_e32 v51, v51
	v_cvt_pk_bf16_f32 v187, v192, v193
	ds_write2st64_b32 v94, v54, v187 offset1:68
	v_mov_b32_e32 v54, v188
	v_mov_b32_e32 v55, v192
	v_mov_b32_e32 v192, v189
	v_pk_fma_f32 v[188:189], v[70:71], v[104:105], v[108:109]
	v_lshlrev_b32_e32 v108, 16, v125
	v_and_b32_e32 v109, 0xffff0000, v125
	v_pk_fma_f32 v[188:189], v[62:63], v[108:109], v[188:189]
	v_pk_mul_f32 v[54:55], v[50:51], v[54:55]
	v_mul_f32_e32 v187, 0xbfb8aa3b, v188
	v_exp_f32_e32 v187, v187
	v_pk_mul_f32 v[50:51], v[50:51], v[192:193]
	v_pk_fma_f32 v[110:111], v[60:61], v[110:111], v[76:77]
	v_pk_fma_f32 v[78:79], v[58:59], v[78:79], v[74:75]
	v_add_f32_e32 v187, 1.0, v187
	v_rcp_f32_e32 v192, v187
	v_mul_f32_e32 v187, 0xbfb8aa3b, v189
	v_exp_f32_e32 v187, v187
	v_pk_fma_f32 v[110:111], v[68:69], v[80:81], v[110:111]
	v_pk_fma_f32 v[78:79], v[66:67], v[104:105], v[78:79]
	v_pk_fma_f32 v[190:191], v[72:73], v[106:107], v[110:111]
	v_lshlrev_b32_e32 v110, 16, v126
	v_and_b32_e32 v111, 0xffff0000, v126
	v_pk_fma_f32 v[190:191], v[64:65], v[110:111], v[190:191]
	v_add_f32_e32 v187, 1.0, v187
	v_rcp_f32_e32 v193, v187
	v_mul_f32_e32 v187, 0xbfb8aa3b, v190
	v_exp_f32_e32 v187, v187
	v_sub_f32_e32 v52, v184, v52
	v_pk_mul_f32 v[188:189], v[188:189], v[192:193]
	v_add_f32_e32 v52, v52, v56
	v_add_f32_e32 v187, 1.0, v187
	v_rcp_f32_e32 v192, v187
	v_mul_f32_e32 v187, 0xbfb8aa3b, v191
	v_exp_f32_e32 v187, v187
	v_pk_mul_f32 v[188:189], v[188:189], s[80:81] op_sel_hi:[1,0]
	v_pk_fma_f32 v[80:81], v[60:61], v[80:81], v[76:77]
	v_pk_fma_f32 v[104:105], v[58:59], v[104:105], v[74:75]
	v_add_f32_e32 v187, 1.0, v187
	v_rcp_f32_e32 v193, v187
	v_cvt_pk_bf16_f32 v187, v188, v189
	v_pk_fma_f32 v[80:81], v[68:69], v[106:107], v[80:81]
	v_pk_fma_f32 v[104:105], v[66:67], v[108:109], v[104:105]
	v_pk_mul_f32 v[190:191], v[190:191], v[192:193]
	v_pk_fma_f32 v[192:193], v[72:73], v[110:111], v[80:81]
	v_cvt_pk_bf16_f32 v188, v190, v191
	ds_write2st64_b32 v93, v187, v188 offset1:68
	v_pk_fma_f32 v[188:189], v[70:71], v[108:109], v[78:79]
	v_lshlrev_b32_e32 v78, 16, v127
	v_and_b32_e32 v79, 0xffff0000, v127
	v_pk_fma_f32 v[188:189], v[62:63], v[78:79], v[188:189]
	v_lshlrev_b32_e32 v80, 16, v128
	v_mul_f32_e32 v56, 0xbfb8aa3b, v188
	v_exp_f32_e32 v56, v56
	v_and_b32_e32 v81, 0xffff0000, v128
	v_pk_fma_f32 v[192:193], v[64:65], v[80:81], v[192:193]
	v_sub_f32_e32 v53, v184, v53
	v_add_f32_e32 v56, 1.0, v56
	v_rcp_f32_e32 v210, v56
	v_mul_f32_e32 v56, 0xbfb8aa3b, v189
	v_exp_f32_e32 v56, v56
	v_add_f32_e32 v53, v53, v57
	v_mul_f32_e32 v52, 0x3fb8aa3b, v52
	v_mul_f32_e32 v53, 0x3fb8aa3b, v53
	v_add_f32_e32 v56, 1.0, v56
	v_rcp_f32_e32 v211, v56
	v_mul_f32_e32 v56, 0xbfb8aa3b, v192
	v_exp_f32_e32 v56, v56
	v_exp_f32_e32 v52, v52
	v_pk_mul_f32 v[188:189], v[188:189], v[210:211]
	v_exp_f32_e32 v53, v53
	v_add_f32_e32 v56, 1.0, v56
	v_rcp_f32_e32 v210, v56
	v_mul_f32_e32 v56, 0xbfb8aa3b, v193
	v_exp_f32_e32 v56, v56
	v_pk_mul_f32 v[188:189], v[188:189], s[80:81] op_sel_hi:[1,0]
	v_pk_fma_f32 v[106:107], v[60:61], v[106:107], v[76:77]
	v_pk_fma_f32 v[108:109], v[58:59], v[108:109], v[74:75]
	v_add_f32_e32 v56, 1.0, v56
	v_rcp_f32_e32 v211, v56
	v_cvt_pk_bf16_f32 v56, v188, v189
	v_pk_fma_f32 v[188:189], v[70:71], v[78:79], v[104:105]
	v_lshlrev_b32_e32 v104, 16, v129
	v_pk_mul_f32 v[192:193], v[192:193], v[210:211]
	v_and_b32_e32 v105, 0xffff0000, v129
	v_cvt_pk_bf16_f32 v187, v192, v193
	v_pk_fma_f32 v[188:189], v[62:63], v[104:105], v[188:189]
	ds_write2st64_b32 v95, v56, v187 offset1:68
	v_mul_f32_e32 v187, 0xbfb8aa3b, v188
	v_exp_f32_e32 v187, v187
	v_mov_b32_e32 v56, v190
	v_mov_b32_e32 v57, v192
	v_mov_b32_e32 v192, v191
	v_add_f32_e32 v187, 1.0, v187
	v_pk_mul_f32 v[56:57], v[56:57], v[52:53]
	v_pk_mul_f32 v[52:53], v[192:193], v[52:53]
	v_rcp_f32_e32 v192, v187
	v_mul_f32_e32 v187, 0xbfb8aa3b, v189
	v_exp_f32_e32 v187, v187
	v_pk_fma_f32 v[106:107], v[68:69], v[110:111], v[106:107]
	v_pk_fma_f32 v[108:109], v[66:67], v[78:79], v[108:109]
	v_pk_fma_f32 v[190:191], v[72:73], v[80:81], v[106:107]
	v_lshlrev_b32_e32 v106, 16, v131
	v_and_b32_e32 v107, 0xffff0000, v131
	v_pk_fma_f32 v[190:191], v[64:65], v[106:107], v[190:191]
	v_add_f32_e32 v187, 1.0, v187
	v_rcp_f32_e32 v193, v187
	v_mul_f32_e32 v187, 0xbfb8aa3b, v190
	v_exp_f32_e32 v187, v187
	v_pk_fma_f32 v[108:109], v[70:71], v[104:105], v[108:109]
	v_pk_mul_f32 v[188:189], v[188:189], v[192:193]
	v_sub_f32_e32 v42, v184, v42
	v_add_f32_e32 v187, 1.0, v187
	v_rcp_f32_e32 v192, v187
	v_mul_f32_e32 v187, 0xbfb8aa3b, v191
	v_exp_f32_e32 v187, v187
	v_pk_mul_f32 v[188:189], v[188:189], s[80:81] op_sel_hi:[1,0]
	s_waitcnt lgkmcnt(3)
; #define LAS __attribute__((address_space(3)))
; __device__ __forceinline__ unsigned pk2(float lo, float hi) { const f32x2 v = {lo, hi}; const bf16x2n b = __builtin_convertvector(v, bf16x2n); return __builtin_bit_cast(unsigned, b); }
; __device__ __forceinline__ float siluf_(float x) { return x * rcp_(1.0f + __expf(-x)); }
; __device__ __forceinline__ void ml_block(KP p, int e, int b, int hd, int half, LAS unsigned char* lds, const bf16_t* P, bf16_t* YB) {
;     ...
;                 const float q0 = siluf_(aq.x) * qscale, q1 = siluf_(aq.y) * qscale, k0 = siluf_(ak.x), k1 = siluf_(ak.y);
;                 *(LAS unsigned*)(Qs + j * 136 + 2 * d2) = pk2(q0, q1);
;                 *(LAS unsigned*)(Ks + j * 136 + 2 * d2) = pk2(k0, k1);
;                 const float wkj = __expf(blast - Bc[j] + Ip[j]);
;                 kw0[i] = wkj * k0; kw1[i] = wkj * k1;
;             }
;             { u32x4 w; w.x = pk2(kw0[0], kw0[1]); w.y = pk2(kw0[2], kw0[3]); w.z = pk2(kw0[4], kw0[5]); w.w = pk2(kw0[6], kw0[7]); *(LAS u32x4*)(KwT + (2 * d2) * 72 + tg * 8) = w; }
;             { u32x4 w; w.x = pk2(kw1[0], kw1[1]); w.y = pk2(kw1[2], kw1[3]); w.z = pk2(kw1[4], kw1[5]); w.w = pk2(kw1[6], kw1[7]); *(LAS u32x4*)(KwT + (2 * d2 + 1) * 72 + tg * 8) = w; }
;             { u32x4 w; w.x = (vr[0] & 0xFFFFu) | (vr[1] << 16); w.y = (vr[2] & 0xFFFFu) | (vr[3] << 16); w.z = (vr[4] & 0xFFFFu) | (vr[5] << 16); w.w = (vr[6] & 0xFFFFu) | (vr[7] << 16); *(LAS u32x4*)(VT + (2 * d2) * 72 + tg * 8) = w; }
;             { u32x4 w; w.x = (vr[0] >> 16) | (vr[1] & 0xFFFF0000u); w.y = (vr[2] >> 16) | (vr[3] & 0xFFFF0000u); w.z = (vr[4] >> 16) | (vr[5] & 0xFFFF0000u); w.w = (vr[6] >> 16) | (vr[7] & 0xFFFF0000u); *(LAS u32x4*)(VT + (2 * d2 + 1) * 72 + tg * 8) = w; }
	v_add_f32_e32 v42, v42, v46
	v_pk_fma_f32 v[110:111], v[60:61], v[110:111], v[76:77]
	v_add_f32_e32 v187, 1.0, v187
	v_rcp_f32_e32 v193, v187
	v_cvt_pk_bf16_f32 v187, v188, v189
	v_and_b32_e32 v189, 0xffff0000, v132
	v_pk_fma_f32 v[110:111], v[68:69], v[80:81], v[110:111]
	v_pk_mul_f32 v[190:191], v[190:191], v[192:193]
	v_pk_fma_f32 v[110:111], v[72:73], v[106:107], v[110:111]
	v_cvt_pk_bf16_f32 v188, v190, v191
	ds_write2st64_b32 v159, v187, v188 offset1:68
	v_lshlrev_b32_e32 v188, 16, v132
	v_pk_fma_f32 v[108:109], v[62:63], v[188:189], v[108:109]
	v_lshlrev_b32_e32 v192, 16, v133
	v_mul_f32_e32 v46, 0xbfb8aa3b, v108
	v_exp_f32_e32 v46, v46
	v_and_b32_e32 v193, 0xffff0000, v133
	v_pk_fma_f32 v[110:111], v[64:65], v[192:193], v[110:111]
	v_pk_fma_f32 v[78:79], v[58:59], v[78:79], v[74:75]
	v_add_f32_e32 v46, 1.0, v46
	v_rcp_f32_e32 v210, v46
	v_mul_f32_e32 v46, 0xbfb8aa3b, v109
	v_exp_f32_e32 v46, v46
	v_pk_fma_f32 v[58:59], v[58:59], v[104:105], v[74:75]
	v_pk_fma_f32 v[78:79], v[66:67], v[104:105], v[78:79]
	v_pk_fma_f32 v[58:59], v[66:67], v[188:189], v[58:59]
	v_add_f32_e32 v46, 1.0, v46
	v_rcp_f32_e32 v211, v46
	v_mul_f32_e32 v46, 0xbfb8aa3b, v110
	v_exp_f32_e32 v46, v46
	v_pk_fma_f32 v[78:79], v[70:71], v[188:189], v[78:79]
	v_pk_mul_f32 v[108:109], v[108:109], v[210:211]
	v_lshlrev_b32_e32 v66, 16, v136
	v_add_f32_e32 v46, 1.0, v46
	v_rcp_f32_e32 v210, v46
	v_mul_f32_e32 v46, 0xbfb8aa3b, v111
	v_exp_f32_e32 v46, v46
	v_pk_mul_f32 v[108:109], v[108:109], s[80:81] op_sel_hi:[1,0]
	v_and_b32_e32 v67, 0xffff0000, v136
	v_sub_f32_e32 v44, v184, v44
	v_add_f32_e32 v46, 1.0, v46
	v_rcp_f32_e32 v211, v46
	v_cvt_pk_bf16_f32 v46, v108, v109
	v_and_b32_e32 v109, 0xffff0000, v134
	v_add_f32_e32 v44, v44, v48
	v_pk_mul_f32 v[110:111], v[110:111], v[210:211]
	v_sub_f32_e32 v43, v184, v43
	v_cvt_pk_bf16_f32 v108, v110, v111
	ds_write2st64_b32 v160, v46, v108 offset1:68
	v_lshlrev_b32_e32 v108, 16, v134
	v_pk_fma_f32 v[58:59], v[70:71], v[108:109], v[58:59]
	v_pk_fma_f32 v[78:79], v[62:63], v[108:109], v[78:79]
	v_pk_fma_f32 v[58:59], v[62:63], v[66:67], v[58:59]
	v_mul_f32_e32 v187, 0xbfb8aa3b, v78
	v_mul_f32_e32 v48, 0xbfb8aa3b, v58
	v_exp_f32_e32 v187, v187
	v_exp_f32_e32 v48, v48
	v_add_f32_e32 v43, v43, v47
	v_mul_f32_e32 v42, 0x3fb8aa3b, v42
	v_mul_f32_e32 v43, 0x3fb8aa3b, v43
	v_exp_f32_e32 v42, v42
	v_exp_f32_e32 v43, v43
	v_add_f32_e32 v187, 1.0, v187
	v_add_f32_e32 v48, 1.0, v48
	v_mov_b32_e32 v46, v190
	v_rcp_f32_e32 v190, v187
	v_mul_f32_e32 v187, 0xbfb8aa3b, v79
	v_rcp_f32_e32 v62, v48
	v_mul_f32_e32 v48, 0xbfb8aa3b, v59
	v_exp_f32_e32 v187, v187
	v_exp_f32_e32 v48, v48
	v_mov_b32_e32 v47, v110
	v_mov_b32_e32 v110, v191
	v_pk_fma_f32 v[80:81], v[60:61], v[80:81], v[76:77]
	v_pk_fma_f32 v[60:61], v[60:61], v[106:107], v[76:77]
	v_pk_mul_f32 v[46:47], v[46:47], v[42:43]
	v_pk_mul_f32 v[42:43], v[110:111], v[42:43]
	v_pk_fma_f32 v[80:81], v[68:69], v[106:107], v[80:81]
	v_lshlrev_b32_e32 v110, 16, v135
	v_and_b32_e32 v111, 0xffff0000, v135
	v_pk_fma_f32 v[60:61], v[68:69], v[192:193], v[60:61]
	v_pk_fma_f32 v[80:81], v[72:73], v[192:193], v[80:81]
	v_pk_fma_f32 v[60:61], v[72:73], v[110:111], v[60:61]
	v_lshlrev_b32_e32 v68, 16, v137
	v_and_b32_e32 v69, 0xffff0000, v137
	v_pk_fma_f32 v[80:81], v[64:65], v[110:111], v[80:81]
	v_add_f32_e32 v187, 1.0, v187
	v_pk_fma_f32 v[60:61], v[64:65], v[68:69], v[60:61]
	v_add_f32_e32 v48, 1.0, v48
	v_rcp_f32_e32 v191, v187
	v_mul_f32_e32 v187, 0xbfb8aa3b, v80
	v_rcp_f32_e32 v63, v48
	v_mul_f32_e32 v48, 0xbfb8aa3b, v60
	v_exp_f32_e32 v187, v187
	v_exp_f32_e32 v48, v48
	v_pk_mul_f32 v[78:79], v[78:79], v[190:191]
	v_pk_mul_f32 v[58:59], v[58:59], v[62:63]
	v_add_f32_e32 v187, 1.0, v187
	v_add_f32_e32 v48, 1.0, v48
	v_rcp_f32_e32 v190, v187
	v_mul_f32_e32 v187, 0xbfb8aa3b, v81
	v_rcp_f32_e32 v62, v48
	v_mul_f32_e32 v48, 0xbfb8aa3b, v61
	v_exp_f32_e32 v187, v187
	v_exp_f32_e32 v48, v48
	v_sub_f32_e32 v45, v184, v45
	v_add_f32_e32 v45, v45, v49
	v_add_f32_e32 v187, 1.0, v187
	v_add_f32_e32 v48, 1.0, v48
	v_rcp_f32_e32 v191, v187
	v_rcp_f32_e32 v63, v48
	v_mul_f32_e32 v44, 0x3fb8aa3b, v44
	v_mul_f32_e32 v45, 0x3fb8aa3b, v45
	v_exp_f32_e32 v44, v44
	v_exp_f32_e32 v45, v45
	v_pk_mul_f32 v[78:79], v[78:79], s[80:81] op_sel_hi:[1,0]
	v_pk_mul_f32 v[80:81], v[80:81], v[190:191]
	v_pk_mul_f32 v[58:59], v[58:59], s[80:81] op_sel_hi:[1,0]
	v_pk_mul_f32 v[60:61], v[60:61], v[62:63]
	v_cvt_pk_bf16_f32 v78, v78, v79
	v_cvt_pk_bf16_f32 v79, v80, v81
	v_cvt_pk_bf16_f32 v48, v58, v59
	v_cvt_pk_bf16_f32 v58, v60, v61
	ds_write2st64_b32 v161, v78, v79 offset1:68
	ds_write2st64_b32 v162, v48, v58 offset1:68
	v_mov_b32_e32 v48, v80
	v_mov_b32_e32 v49, v60
	v_pk_mul_f32 v[48:49], v[48:49], v[44:45]
	v_mov_b32_e32 v60, v81
	v_pk_mul_f32 v[58:59], v[60:61], v[44:45]
	v_cvt_pk_bf16_f32 v44, v54, v55
	v_cvt_pk_bf16_f32 v45, v56, v57
	v_cvt_pk_bf16_f32 v46, v46, v47
	v_cvt_pk_bf16_f32 v47, v48, v49
	ds_write_b128 v85, v[44:47] offset:44032
	v_cvt_pk_bf16_f32 v44, v50, v51
	v_cvt_pk_bf16_f32 v45, v52, v53
	v_cvt_pk_bf16_f32 v46, v42, v43
	v_cvt_pk_bf16_f32 v47, v58, v59
	ds_write_b128 v85, v[44:47] offset:44176
	s_waitcnt vmcnt(7)
	v_and_b32_e32 v42, 0xffff, v178
	s_waitcnt vmcnt(5)
	v_and_b32_e32 v43, 0xffff, v180
	s_waitcnt vmcnt(3)
	v_and_b32_e32 v44, 0xffff, v182
	s_waitcnt vmcnt(1)
	v_and_b32_e32 v45, 0xffff, v185
	v_lshl_or_b32 v42, v179, 16, v42
	v_lshl_or_b32 v43, v181, 16, v43
	v_lshl_or_b32 v44, v183, 16, v44
	s_waitcnt vmcnt(0)
	v_lshl_or_b32 v45, v186, 16, v45
	ds_write_b128 v85, v[42:45] offset:62464
	v_lshrrev_b32_e32 v42, 16, v178
	v_lshrrev_b32_e32 v43, 16, v180
	v_lshrrev_b32_e32 v44, 16, v182
	v_lshrrev_b32_e32 v45, 16, v185
	s_cmpk_eq_i32 s52, 0xfc0
	v_and_or_b32 v42, v179, s5, v42
	v_and_or_b32 v43, v181, s5, v43
	v_and_or_b32 v44, v183, s5, v44
	v_and_or_b32 v45, v186, s5, v45
	ds_write_b128 v85, v[42:45] offset:62608
	s_cbranch_scc1 .LBB0_351
; __device__ __forceinline__ void ml_block(KP p, int e, int b, int hd, int half, LAS unsigned char* lds, const bf16_t* P, bf16_t* YB) {
;     ...
;     auto load_qkv = [&](int tb) {
;         const int tstart = tb + tg * 8;
; #pragma unroll
;         for (int j = 0; j < 11; ++j) {
;             const int t = tstart - 3 + j;
;             if (t >= 0) { const bf16_t* row = P + (rbase + t) * NPROJ; qr[j] = *(const unsigned*)(row + 1024 + cq); kr[j] = *(const unsigned*)(row + 1024 + ck); }
;             else { qr[j] = 0u; kr[j] = 0u; }
;         }
;     ...
;         if (has_next) load_qkv(tb + 64);
	v_add_u32_e32 v44, s52, v167
	v_add_u32_e32 v45, 0xffff003d, v44
	v_mad_u64_u32 v[46:47], s[78:79], v45, s81, v[96:97]
	s_nop 4
	s_mov_b64 s[78:79], 0x1a00
	global_load_dword v113, v[46:47], off offset:2048
	global_load_dword v115, v[46:47], off offset:3072
	v_lshl_add_u64 v[42:43], v[46:47], 0, s[78:79]
	global_load_dword v116, v[42:43], off offset:2048
	global_load_dword v117, v[42:43], off offset:3072
	v_lshl_add_u64 v[46:47], v[42:43], 0, s[78:79]
	global_load_dword v118, v[46:47], off offset:2048
	global_load_dword v119, v[46:47], off offset:3072
	v_lshl_add_u64 v[42:43], v[46:47], 0, s[78:79]
	global_load_dword v120, v[42:43], off offset:2048
	global_load_dword v121, v[42:43], off offset:3072
	v_lshl_add_u64 v[46:47], v[42:43], 0, s[78:79]
	global_load_dword v122, v[46:47], off offset:2048
	global_load_dword v123, v[46:47], off offset:3072
	v_lshl_add_u64 v[42:43], v[46:47], 0, s[78:79]
	global_load_dword v125, v[42:43], off offset:2048
	global_load_dword v126, v[42:43], off offset:3072
	v_lshl_add_u64 v[46:47], v[42:43], 0, s[78:79]
	global_load_dword v127, v[46:47], off offset:2048
	global_load_dword v128, v[46:47], off offset:3072
	v_lshl_add_u64 v[42:43], v[46:47], 0, s[78:79]
	global_load_dword v129, v[42:43], off offset:2048
	global_load_dword v131, v[42:43], off offset:3072
	v_lshl_add_u64 v[46:47], v[42:43], 0, s[78:79]
	global_load_dword v132, v[46:47], off offset:2048
	global_load_dword v133, v[46:47], off offset:3072
	v_lshl_add_u64 v[42:43], v[46:47], 0, s[78:79]
	global_load_dword v134, v[42:43], off offset:2048
	global_load_dword v135, v[42:43], off offset:3072
	v_lshl_add_u64 v[46:47], v[42:43], 0, s[78:79]
	global_load_dword v136, v[46:47], off offset:2048
	global_load_dword v137, v[46:47], off offset:3072
